# GEMM epilogues de-serialized: SWIGLU/W_in row-scale partial-sum loads issued together (fast path np=16), residual epilogue (bf16 residual, bf16 out) hand-written with 16 loads up front and counted vmc
# speedup vs baseline: 1.0074x; 1.0074x over previous
;     static __device__ __forceinline__ float rowsum(const float* ssq, int row, int np) {
;         const f32x4* p = (const f32x4*)(ssq + (size_t)row * np);
;         float s = 0.f;
;         for (int i = 0; i < np / 4; ++i) { const f32x4 v = p[i]; s += (v[0] + v[1]) + (v[2] + v[3]); }
;         return s;
;     }
;     __device__ __forceinline__ void row_scales(int rowbase, int lane, int fr, float (&rs)[2]) const {
;         rs[0] = rsqrtf(rowsum(ssq, rowbase + lane, np) * inv_dim + EPS); rs[1] = rsqrtf(rowsum(ssq, rowbase + 128 + lane, np) * inv_dim + EPS);
;     }
.LBB0_463:
	s_andn2_b64 vcc, exec, s[6:7]
	s_cbranch_vccnz .LBB0_804
	s_cmp_lt_i32 s67, 1
	s_mov_b64 s[6:7], -1
	s_cbranch_scc1 .LBB0_796
	s_cmp_gt_i32 s67, 1
	s_cbranch_scc0 .LBB0_649
	v_readlane_b32 s6, v255, 16
	v_readlane_b32 s7, v255, 17
	v_add_u32_e32 v3, s2, v194
	v_ashrrev_i32_e32 v134, 31, v3
	v_cndmask_b32_e64 v0, 0, 1, s[6:7]
	v_cmp_ne_u32_e64 s[40:41], 1, v0
	s_andn2_b64 vcc, exec, s[6:7]
	v_mov_b32_e32 v0, 0
	s_cbranch_vccnz .LBB0_469
	v_readlane_b32 s6, v255, 22
	v_readlane_b32 s7, v255, 23
	v_readlane_b32 s14, v255, 61
	v_readlane_b32 s15, v255, 62
	v_mov_b64_e32 v[132:133], s[6:7]
	v_mad_u64_u32 v[132:133], s[6:7], s14, v3, v[132:133]
	v_mul_lo_u32 v0, s14, v134
	v_mul_lo_u32 v134, s15, v3
	v_add3_u32 v133, v134, v133, v0
	v_mov_b32_e32 v0, 0
	v_readlane_b32 s1, v255, 42
	s_cmp_lg_u32 s1, 4
	s_cbranch_scc1 .LBB0_468
	global_load_dwordx4 v[160:163], v[132:133], off
	global_load_dwordx4 v[164:167], v[132:133], off offset:16
	global_load_dwordx4 v[168:171], v[132:133], off offset:32
	global_load_dwordx4 v[172:175], v[132:133], off offset:48
	v_add_u32_e32 v3, 0x80, v3
	v_readlane_b32 s6, v255, 22
	v_ashrrev_i32_e32 v132, 31, v3
	v_readlane_b32 s14, v255, 61
	v_readlane_b32 s7, v255, 23
	v_readlane_b32 s15, v255, 62
	v_mul_lo_u32 v134, s14, v132
	v_mov_b64_e32 v[132:133], s[6:7]
	v_mul_lo_u32 v135, s15, v3
	v_mad_u64_u32 v[132:133], s[6:7], s14, v3, v[132:133]
	v_add3_u32 v133, v135, v133, v134
	global_load_dwordx4 v[176:179], v[132:133], off
	global_load_dwordx4 v[180:183], v[132:133], off offset:16
	global_load_dwordx4 v[202:205], v[132:133], off offset:32
	global_load_dwordx4 v[206:209], v[132:133], off offset:48
	v_mov_b32_e32 v197, 0
	s_waitcnt vmcnt(4)
	v_add_f32_e32 v134, v160, v161
	v_add_f32_e32 v136, v162, v163
	v_add_f32_e32 v134, v134, v136
	v_add_f32_e32 v0, v0, v134
	v_add_f32_e32 v134, v164, v165
	v_add_f32_e32 v136, v166, v167
	v_add_f32_e32 v134, v134, v136
	v_add_f32_e32 v0, v0, v134
	v_add_f32_e32 v134, v168, v169
	v_add_f32_e32 v136, v170, v171
	v_add_f32_e32 v134, v134, v136
	v_add_f32_e32 v0, v0, v134
	v_add_f32_e32 v134, v172, v173
	v_add_f32_e32 v136, v174, v175
	v_add_f32_e32 v134, v134, v136
	v_add_f32_e32 v0, v0, v134
	s_waitcnt vmcnt(0)
	v_add_f32_e32 v134, v176, v177
	v_add_f32_e32 v136, v178, v179
	v_add_f32_e32 v3, v134, v136
	v_add_f32_e32 v197, v197, v3
	v_add_f32_e32 v134, v180, v181
	v_add_f32_e32 v136, v182, v183
	v_add_f32_e32 v3, v134, v136
	v_add_f32_e32 v197, v197, v3
	v_add_f32_e32 v134, v202, v203
	v_add_f32_e32 v136, v204, v205
	v_add_f32_e32 v3, v134, v136
	v_add_f32_e32 v197, v197, v3
	v_add_f32_e32 v134, v206, v207
	v_add_f32_e32 v136, v208, v209
	v_add_f32_e32 v3, v134, v136
	v_add_f32_e32 v197, v197, v3
	s_branch .LBB0_472

; __device__ __forceinline__ float bf_lo(unsigned w) { return __uint_as_float(w << 16); }
; __device__ __forceinline__ float bf_hi(unsigned w) { return __uint_as_float(w & 0xffff0000u); }
;     static __device__ __forceinline__ u32x4 pack8(const f32x4 a, const f32x4 b) { u32x4 w; w.x = cvtpk(a[0], a[1]); w.y = cvtpk(a[2], a[3]); w.z = cvtpk(b[0], b[1]); w.w = cvtpk(b[2], b[3]); return w; }
;     __device__ __forceinline__ void operator()(const f32x4 (&acc)[2][2][4][2], const pg8::Unit& u, int wr, int wc, int fr_, int fq_) const {
;     ...
;         } else if (MEN(1) && mode == M_RESID) {
;             const float* res = (const float*)i0; const bf16_t* resb = (const bf16_t*)i0; float* outp = (float*)o0; bf16_t* xb = (bf16_t*)o1; const bool rb16 = np == 0;
; #pragma unroll
;             for (int ai = 0; ai < 2; ++ai)
; #pragma unroll
;                 for (int m = 0; m < 4; ++m) {
;                     const int row = rowbase + ai * 128 + m * 16 + fr; float s = 0.f;
; #pragma unroll
;                     for (int bj = 0; bj < 2; ++bj) {
;                         const size_t off = (size_t)row * DM + u.pn * 256 + bj * 128 + cw;
;                         f32x4 a, b;
;                         if (rb16) { const u32x4 w = *(const u32x4*)(resb + off); a = (f32x4){bf_lo(w.x), bf_hi(w.x), bf_lo(w.y), bf_hi(w.y)}; b = (f32x4){bf_lo(w.z), bf_hi(w.z), bf_lo(w.w), bf_hi(w.w)}; }
;                         else { a = *(const f32x4*)(res + off); b = *(const f32x4*)(res + off + 4); }
;                         const f32x4 v0 = a + acc[ai][bj][m][0] * f0, v1 = b + acc[ai][bj][m][1] * f0;
;                         if (outp) { *(f32x4*)(outp + off) = v0; *(f32x4*)(outp + off + 4) = v1; }
;                         if (xb) *(u32x4*)(xb + off) = pack8(v0, v1);
;                         s += (v0[0] * v0[0] + v0[1] * v0[1]) + (v0[2] * v0[2] + v0[3] * v0[3]) + (v1[0] * v1[0] + v1[1] * v1[1]) + (v1[2] * v1[2] + v1[3] * v1[3]);
;                     }
;                     s += __shfl_xor(s, 16); s += __shfl_xor(s, 32);
;                     if (fq == 0) ssq_out[(size_t)row * 16 + u.pn * 4 + wc] = s;
;                 }
.LBB0_649:
	s_and_b64 vcc, exec, s[6:7]
	s_cbranch_vccz .LBB0_795
	v_readlane_b32 s14, v255, 25
	v_readlane_b32 s15, v255, 56
	v_readlane_b32 s1, v255, 58
	s_or_b32 s14, s14, s15
	s_cmp_lg_u32 s14, 0
	s_cbranch_scc1 .Lresid_generic
	s_cmp_eq_u32 s1, 0
	s_cbranch_scc1 .Lresid_generic
	v_readlane_b32 s14, v255, 14
	v_readlane_b32 s15, v255, 15
	v_readlane_b32 s40, v255, 18
	v_readlane_b32 s41, v255, 19
	v_readlane_b32 s1, v255, 51
	s_lshl_b32 s16, s36, 2
	v_add_u32_e32 v132, s2, v193
	v_add_u32_e32 v133, s92, v2
	s_add_i32 s16, s16, s1
	s_lshl_b32 s16, s16, 2
	v_lshlrev_b32_e32 v133, 1, v133
	v_lshl_add_u32 v134, v132, 6, s16
	v_lshl_add_u32 v132, v132, 11, v133
	v_xor_b32_e32 v135, 16, v219
	v_xor_b32_e32 v3, 32, v219
	v_lshlrev_b32_e32 v135, 2, v135
	v_lshlrev_b32_e32 v3, 2, v3
	v_cmp_eq_u32_e64 s[46:47], 0, v195
	global_load_dwordx4 v[160:163], v132, s[4:5]
	v_add_u32_e32 v133, 0x100, v132
	global_load_dwordx4 v[164:167], v133, s[4:5]
	v_add_u32_e32 v133, 0x8000, v132
	global_load_dwordx4 v[168:171], v133, s[4:5]
	v_add_u32_e32 v133, 0x8100, v132
	global_load_dwordx4 v[172:175], v133, s[4:5]
	v_add_u32_e32 v133, 0x10000, v132
	global_load_dwordx4 v[176:179], v133, s[4:5]
	v_add_u32_e32 v133, 0x10100, v132
	global_load_dwordx4 v[180:183], v133, s[4:5]
	v_add_u32_e32 v133, 0x18000, v132
	global_load_dwordx4 v[194:197], v133, s[4:5]
	v_add_u32_e32 v133, 0x18100, v132
	global_load_dwordx4 v[198:201], v133, s[4:5]
	v_add_u32_e32 v133, 0x40000, v132
	global_load_dwordx4 v[202:205], v133, s[4:5]
	v_add_u32_e32 v133, 0x40100, v132
	global_load_dwordx4 v[206:209], v133, s[4:5]
	v_add_u32_e32 v133, 0x48000, v132
	global_load_dwordx4 v[210:213], v133, s[4:5]
	v_add_u32_e32 v133, 0x48100, v132
	global_load_dwordx4 v[236:239], v133, s[4:5]
	v_add_u32_e32 v133, 0x50000, v132
	global_load_dwordx4 v[240:243], v133, s[4:5]
	v_add_u32_e32 v133, 0x50100, v132
	global_load_dwordx4 v[244:247], v133, s[4:5]
	v_add_u32_e32 v133, 0x58000, v132
	global_load_dwordx4 v[248:251], v133, s[4:5]
	v_add_u32_e32 v133, 0x58100, v132
	global_load_dwordx4 v[136:139], v133, s[4:5]
	s_waitcnt vmcnt(15)
	v_lshlrev_b32_e32 v140, 16, v160
	v_and_b32_e32 v141, 0xffff0000, v160
	v_lshlrev_b32_e32 v142, 16, v161
	v_and_b32_e32 v143, 0xffff0000, v161
	v_lshlrev_b32_e32 v144, 16, v162
	v_and_b32_e32 v145, 0xffff0000, v162
	v_lshlrev_b32_e32 v146, 16, v163
	v_and_b32_e32 v147, 0xffff0000, v163
	v_pk_fma_f32 v[140:141], s[88:89], v[124:125], v[140:141]
	v_pk_fma_f32 v[142:143], s[88:89], v[126:127], v[142:143]
	v_pk_fma_f32 v[144:145], s[88:89], v[116:117], v[144:145]
	v_pk_fma_f32 v[146:147], s[88:89], v[118:119], v[146:147]
	v_cvt_pk_bf16_f32 v160, v140, v141
	v_cvt_pk_bf16_f32 v161, v142, v143
	v_cvt_pk_bf16_f32 v162, v144, v145
	v_cvt_pk_bf16_f32 v163, v146, v147
	global_store_dwordx4 v132, v[160:163], s[14:15]
	v_mul_f32_e32 v0, v140, v140
	v_mul_f32_e32 v184, v141, v141
	v_fmac_f32_e32 v0, v142, v142
	v_fmac_f32_e32 v184, v143, v143
	v_fmac_f32_e32 v0, v144, v144
	v_fmac_f32_e32 v184, v145, v145
	v_fmac_f32_e32 v0, v146, v146
	v_fmac_f32_e32 v184, v147, v147
	s_waitcnt vmcnt(15)
	v_lshlrev_b32_e32 v140, 16, v164
	v_and_b32_e32 v141, 0xffff0000, v164
	v_lshlrev_b32_e32 v142, 16, v165
	v_and_b32_e32 v143, 0xffff0000, v165
	v_lshlrev_b32_e32 v144, 16, v166
	v_and_b32_e32 v145, 0xffff0000, v166
	v_lshlrev_b32_e32 v146, 16, v167
	v_and_b32_e32 v147, 0xffff0000, v167
	v_pk_fma_f32 v[140:141], s[88:89], v[128:129], v[140:141]
	v_pk_fma_f32 v[142:143], s[88:89], v[130:131], v[142:143]
	v_pk_fma_f32 v[144:145], s[88:89], v[120:121], v[144:145]
	v_pk_fma_f32 v[146:147], s[88:89], v[122:123], v[146:147]
	v_cvt_pk_bf16_f32 v164, v140, v141
	v_cvt_pk_bf16_f32 v165, v142, v143
	v_cvt_pk_bf16_f32 v166, v144, v145
	v_cvt_pk_bf16_f32 v167, v146, v147
	v_add_u32_e32 v133, 0x100, v132
	global_store_dwordx4 v133, v[164:167], s[14:15]
	v_fmac_f32_e32 v0, v140, v140
	v_fmac_f32_e32 v184, v141, v141
	v_fmac_f32_e32 v0, v142, v142
	v_fmac_f32_e32 v184, v143, v143
	v_fmac_f32_e32 v0, v144, v144
	v_fmac_f32_e32 v184, v145, v145
	v_fmac_f32_e32 v0, v146, v146
	v_fmac_f32_e32 v184, v147, v147
	v_add_f32_e32 v0, v0, v184
	ds_bpermute_b32 v133, v135, v0
	s_waitcnt lgkmcnt(0)
	v_add_f32_e32 v0, v0, v133
	ds_bpermute_b32 v133, v3, v0
	s_waitcnt lgkmcnt(0)
	v_add_f32_e32 v0, v0, v133
	s_and_saveexec_b64 s[6:7], s[46:47]
	global_store_dword v134, v0, s[40:41]
	s_or_b64 exec, exec, s[6:7]
	s_waitcnt vmcnt(16)
	v_lshlrev_b32_e32 v140, 16, v168
	v_and_b32_e32 v141, 0xffff0000, v168
	v_lshlrev_b32_e32 v142, 16, v169
	v_and_b32_e32 v143, 0xffff0000, v169
	v_lshlrev_b32_e32 v144, 16, v170
	v_and_b32_e32 v145, 0xffff0000, v170
	v_lshlrev_b32_e32 v146, 16, v171
	v_and_b32_e32 v147, 0xffff0000, v171
	v_pk_fma_f32 v[140:141], s[88:89], v[108:109], v[140:141]
	v_pk_fma_f32 v[142:143], s[88:89], v[110:111], v[142:143]
	v_pk_fma_f32 v[144:145], s[88:89], v[100:101], v[144:145]
	v_pk_fma_f32 v[146:147], s[88:89], v[102:103], v[146:147]
	v_cvt_pk_bf16_f32 v168, v140, v141
	v_cvt_pk_bf16_f32 v169, v142, v143
	v_cvt_pk_bf16_f32 v170, v144, v145
	v_cvt_pk_bf16_f32 v171, v146, v147
	v_add_u32_e32 v133, 0x8000, v132
	global_store_dwordx4 v133, v[168:171], s[14:15]
	v_mul_f32_e32 v0, v140, v140
	v_mul_f32_e32 v184, v141, v141
	v_fmac_f32_e32 v0, v142, v142
	v_fmac_f32_e32 v184, v143, v143
	v_fmac_f32_e32 v0, v144, v144
	v_fmac_f32_e32 v184, v145, v145
	v_fmac_f32_e32 v0, v146, v146
	v_fmac_f32_e32 v184, v147, v147
	s_waitcnt vmcnt(16)
; __device__ __forceinline__ float bf_lo(unsigned w) { return __uint_as_float(w << 16); }
; __device__ __forceinline__ float bf_hi(unsigned w) { return __uint_as_float(w & 0xffff0000u); }
;     static __device__ __forceinline__ u32x4 pack8(const f32x4 a, const f32x4 b) { u32x4 w; w.x = cvtpk(a[0], a[1]); w.y = cvtpk(a[2], a[3]); w.z = cvtpk(b[0], b[1]); w.w = cvtpk(b[2], b[3]); return w; }
;     __device__ __forceinline__ void operator()(const f32x4 (&acc)[2][2][4][2], const pg8::Unit& u, int wr, int wc, int fr_, int fq_) const {
;     ...
;         } else if (MEN(1) && mode == M_RESID) {
;             const float* res = (const float*)i0; const bf16_t* resb = (const bf16_t*)i0; float* outp = (float*)o0; bf16_t* xb = (bf16_t*)o1; const bool rb16 = np == 0;
; #pragma unroll
;             for (int ai = 0; ai < 2; ++ai)
; #pragma unroll
;                 for (int m = 0; m < 4; ++m) {
;                     const int row = rowbase + ai * 128 + m * 16 + fr; float s = 0.f;
; #pragma unroll
;                     for (int bj = 0; bj < 2; ++bj) {
;                         const size_t off = (size_t)row * DM + u.pn * 256 + bj * 128 + cw;
;                         f32x4 a, b;
;                         if (rb16) { const u32x4 w = *(const u32x4*)(resb + off); a = (f32x4){bf_lo(w.x), bf_hi(w.x), bf_lo(w.y), bf_hi(w.y)}; b = (f32x4){bf_lo(w.z), bf_hi(w.z), bf_lo(w.w), bf_hi(w.w)}; }
;                         else { a = *(const f32x4*)(res + off); b = *(const f32x4*)(res + off + 4); }
;                         const f32x4 v0 = a + acc[ai][bj][m][0] * f0, v1 = b + acc[ai][bj][m][1] * f0;
;                         if (outp) { *(f32x4*)(outp + off) = v0; *(f32x4*)(outp + off + 4) = v1; }
;                         if (xb) *(u32x4*)(xb + off) = pack8(v0, v1);
;                         s += (v0[0] * v0[0] + v0[1] * v0[1]) + (v0[2] * v0[2] + v0[3] * v0[3]) + (v1[0] * v1[0] + v1[1] * v1[1]) + (v1[2] * v1[2] + v1[3] * v1[3]);
;                     }
;                     s += __shfl_xor(s, 16); s += __shfl_xor(s, 32);
;                     if (fq == 0) ssq_out[(size_t)row * 16 + u.pn * 4 + wc] = s;
;                 }
	v_lshlrev_b32_e32 v140, 16, v172
	v_and_b32_e32 v141, 0xffff0000, v172
	v_lshlrev_b32_e32 v142, 16, v173
	v_and_b32_e32 v143, 0xffff0000, v173
	v_lshlrev_b32_e32 v144, 16, v174
	v_and_b32_e32 v145, 0xffff0000, v174
	v_lshlrev_b32_e32 v146, 16, v175
	v_and_b32_e32 v147, 0xffff0000, v175
	v_pk_fma_f32 v[140:141], s[88:89], v[112:113], v[140:141]
	v_pk_fma_f32 v[142:143], s[88:89], v[114:115], v[142:143]
	v_pk_fma_f32 v[144:145], s[88:89], v[104:105], v[144:145]
	v_pk_fma_f32 v[146:147], s[88:89], v[106:107], v[146:147]
	v_cvt_pk_bf16_f32 v172, v140, v141
	v_cvt_pk_bf16_f32 v173, v142, v143
	v_cvt_pk_bf16_f32 v174, v144, v145
	v_cvt_pk_bf16_f32 v175, v146, v147
	v_add_u32_e32 v133, 0x8100, v132
	global_store_dwordx4 v133, v[172:175], s[14:15]
	v_fmac_f32_e32 v0, v140, v140
	v_fmac_f32_e32 v184, v141, v141
	v_fmac_f32_e32 v0, v142, v142
	v_fmac_f32_e32 v184, v143, v143
	v_fmac_f32_e32 v0, v144, v144
	v_fmac_f32_e32 v184, v145, v145
	v_fmac_f32_e32 v0, v146, v146
	v_fmac_f32_e32 v184, v147, v147
	v_add_f32_e32 v0, v0, v184
	ds_bpermute_b32 v133, v135, v0
	s_waitcnt lgkmcnt(0)
	v_add_f32_e32 v0, v0, v133
	ds_bpermute_b32 v133, v3, v0
	s_waitcnt lgkmcnt(0)
	v_add_f32_e32 v0, v0, v133
	s_and_saveexec_b64 s[6:7], s[46:47]
	v_add_u32_e32 v133, 0x400, v134
	global_store_dword v133, v0, s[40:41]
	s_or_b64 exec, exec, s[6:7]
	s_waitcnt vmcnt(17)
	v_lshlrev_b32_e32 v140, 16, v176
	v_and_b32_e32 v141, 0xffff0000, v176
	v_lshlrev_b32_e32 v142, 16, v177
	v_and_b32_e32 v143, 0xffff0000, v177
	v_lshlrev_b32_e32 v144, 16, v178
	v_and_b32_e32 v145, 0xffff0000, v178
	v_lshlrev_b32_e32 v146, 16, v179
	v_and_b32_e32 v147, 0xffff0000, v179
	v_pk_fma_f32 v[140:141], s[88:89], v[92:93], v[140:141]
	v_pk_fma_f32 v[142:143], s[88:89], v[94:95], v[142:143]
	v_pk_fma_f32 v[144:145], s[88:89], v[84:85], v[144:145]
	v_pk_fma_f32 v[146:147], s[88:89], v[86:87], v[146:147]
	v_cvt_pk_bf16_f32 v176, v140, v141
	v_cvt_pk_bf16_f32 v177, v142, v143
	v_cvt_pk_bf16_f32 v178, v144, v145
	v_cvt_pk_bf16_f32 v179, v146, v147
	v_add_u32_e32 v133, 0x10000, v132
	global_store_dwordx4 v133, v[176:179], s[14:15]
	v_mul_f32_e32 v0, v140, v140
	v_mul_f32_e32 v184, v141, v141
	v_fmac_f32_e32 v0, v142, v142
	v_fmac_f32_e32 v184, v143, v143
	v_fmac_f32_e32 v0, v144, v144
	v_fmac_f32_e32 v184, v145, v145
	v_fmac_f32_e32 v0, v146, v146
	v_fmac_f32_e32 v184, v147, v147
	s_waitcnt vmcnt(17)
	v_lshlrev_b32_e32 v140, 16, v180
	v_and_b32_e32 v141, 0xffff0000, v180
	v_lshlrev_b32_e32 v142, 16, v181
	v_and_b32_e32 v143, 0xffff0000, v181
	v_lshlrev_b32_e32 v144, 16, v182
	v_and_b32_e32 v145, 0xffff0000, v182
	v_lshlrev_b32_e32 v146, 16, v183
	v_and_b32_e32 v147, 0xffff0000, v183
	v_pk_fma_f32 v[140:141], s[88:89], v[96:97], v[140:141]
	v_pk_fma_f32 v[142:143], s[88:89], v[98:99], v[142:143]
	v_pk_fma_f32 v[144:145], s[88:89], v[88:89], v[144:145]
	v_pk_fma_f32 v[146:147], s[88:89], v[90:91], v[146:147]
	v_cvt_pk_bf16_f32 v180, v140, v141
	v_cvt_pk_bf16_f32 v181, v142, v143
	v_cvt_pk_bf16_f32 v182, v144, v145
	v_cvt_pk_bf16_f32 v183, v146, v147
	v_add_u32_e32 v133, 0x10100, v132
	global_store_dwordx4 v133, v[180:183], s[14:15]
	v_fmac_f32_e32 v0, v140, v140
	v_fmac_f32_e32 v184, v141, v141
	v_fmac_f32_e32 v0, v142, v142
	v_fmac_f32_e32 v184, v143, v143
	v_fmac_f32_e32 v0, v144, v144
	v_fmac_f32_e32 v184, v145, v145
	v_fmac_f32_e32 v0, v146, v146
	v_fmac_f32_e32 v184, v147, v147
	v_add_f32_e32 v0, v0, v184
	ds_bpermute_b32 v133, v135, v0
	s_waitcnt lgkmcnt(0)
	v_add_f32_e32 v0, v0, v133
	ds_bpermute_b32 v133, v3, v0
	s_waitcnt lgkmcnt(0)
	v_add_f32_e32 v0, v0, v133
	s_and_saveexec_b64 s[6:7], s[46:47]
	v_add_u32_e32 v133, 0x800, v134
	global_store_dword v133, v0, s[40:41]
	s_or_b64 exec, exec, s[6:7]
	s_waitcnt vmcnt(18)
	v_lshlrev_b32_e32 v140, 16, v194
	v_and_b32_e32 v141, 0xffff0000, v194
	v_lshlrev_b32_e32 v142, 16, v195
	v_and_b32_e32 v143, 0xffff0000, v195
	v_lshlrev_b32_e32 v144, 16, v196
	v_and_b32_e32 v145, 0xffff0000, v196
	v_lshlrev_b32_e32 v146, 16, v197
	v_and_b32_e32 v147, 0xffff0000, v197
	v_pk_fma_f32 v[140:141], s[88:89], v[76:77], v[140:141]
	v_pk_fma_f32 v[142:143], s[88:89], v[78:79], v[142:143]
	v_pk_fma_f32 v[144:145], s[88:89], v[68:69], v[144:145]
	v_pk_fma_f32 v[146:147], s[88:89], v[70:71], v[146:147]
	v_cvt_pk_bf16_f32 v194, v140, v141
	v_cvt_pk_bf16_f32 v195, v142, v143
	v_cvt_pk_bf16_f32 v196, v144, v145
	v_cvt_pk_bf16_f32 v197, v146, v147
	v_add_u32_e32 v133, 0x18000, v132
	global_store_dwordx4 v133, v[194:197], s[14:15]
	v_mul_f32_e32 v0, v140, v140
	v_mul_f32_e32 v184, v141, v141
	v_fmac_f32_e32 v0, v142, v142
	v_fmac_f32_e32 v184, v143, v143
	v_fmac_f32_e32 v0, v144, v144
	v_fmac_f32_e32 v184, v145, v145
	v_fmac_f32_e32 v0, v146, v146
	v_fmac_f32_e32 v184, v147, v147
	s_waitcnt vmcnt(18)
	v_lshlrev_b32_e32 v140, 16, v198
	v_and_b32_e32 v141, 0xffff0000, v198
	v_lshlrev_b32_e32 v142, 16, v199
	v_and_b32_e32 v143, 0xffff0000, v199
	v_lshlrev_b32_e32 v144, 16, v200
	v_and_b32_e32 v145, 0xffff0000, v200
	v_lshlrev_b32_e32 v146, 16, v201
	v_and_b32_e32 v147, 0xffff0000, v201
	v_pk_fma_f32 v[140:141], s[88:89], v[80:81], v[140:141]
	v_pk_fma_f32 v[142:143], s[88:89], v[82:83], v[142:143]
	v_pk_fma_f32 v[144:145], s[88:89], v[72:73], v[144:145]
	v_pk_fma_f32 v[146:147], s[88:89], v[74:75], v[146:147]
	v_cvt_pk_bf16_f32 v198, v140, v141
	v_cvt_pk_bf16_f32 v199, v142, v143
	v_cvt_pk_bf16_f32 v200, v144, v145
	v_cvt_pk_bf16_f32 v201, v146, v147
	v_add_u32_e32 v133, 0x18100, v132
	global_store_dwordx4 v133, v[198:201], s[14:15]
	v_fmac_f32_e32 v0, v140, v140
	v_fmac_f32_e32 v184, v141, v141
	v_fmac_f32_e32 v0, v142, v142
	v_fmac_f32_e32 v184, v143, v143
	v_fmac_f32_e32 v0, v144, v144
	v_fmac_f32_e32 v184, v145, v145
	v_fmac_f32_e32 v0, v146, v146
	v_fmac_f32_e32 v184, v147, v147
	v_add_f32_e32 v0, v0, v184
	ds_bpermute_b32 v133, v135, v0
	s_waitcnt lgkmcnt(0)
; __device__ __forceinline__ float bf_lo(unsigned w) { return __uint_as_float(w << 16); }
; __device__ __forceinline__ float bf_hi(unsigned w) { return __uint_as_float(w & 0xffff0000u); }
;     static __device__ __forceinline__ u32x4 pack8(const f32x4 a, const f32x4 b) { u32x4 w; w.x = cvtpk(a[0], a[1]); w.y = cvtpk(a[2], a[3]); w.z = cvtpk(b[0], b[1]); w.w = cvtpk(b[2], b[3]); return w; }
;     __device__ __forceinline__ void operator()(const f32x4 (&acc)[2][2][4][2], const pg8::Unit& u, int wr, int wc, int fr_, int fq_) const {
;     ...
;         } else if (MEN(1) && mode == M_RESID) {
;             const float* res = (const float*)i0; const bf16_t* resb = (const bf16_t*)i0; float* outp = (float*)o0; bf16_t* xb = (bf16_t*)o1; const bool rb16 = np == 0;
; #pragma unroll
;             for (int ai = 0; ai < 2; ++ai)
; #pragma unroll
;                 for (int m = 0; m < 4; ++m) {
;                     const int row = rowbase + ai * 128 + m * 16 + fr; float s = 0.f;
; #pragma unroll
;                     for (int bj = 0; bj < 2; ++bj) {
;                         const size_t off = (size_t)row * DM + u.pn * 256 + bj * 128 + cw;
;                         f32x4 a, b;
;                         if (rb16) { const u32x4 w = *(const u32x4*)(resb + off); a = (f32x4){bf_lo(w.x), bf_hi(w.x), bf_lo(w.y), bf_hi(w.y)}; b = (f32x4){bf_lo(w.z), bf_hi(w.z), bf_lo(w.w), bf_hi(w.w)}; }
;                         else { a = *(const f32x4*)(res + off); b = *(const f32x4*)(res + off + 4); }
;                         const f32x4 v0 = a + acc[ai][bj][m][0] * f0, v1 = b + acc[ai][bj][m][1] * f0;
;                         if (outp) { *(f32x4*)(outp + off) = v0; *(f32x4*)(outp + off + 4) = v1; }
;                         if (xb) *(u32x4*)(xb + off) = pack8(v0, v1);
;                         s += (v0[0] * v0[0] + v0[1] * v0[1]) + (v0[2] * v0[2] + v0[3] * v0[3]) + (v1[0] * v1[0] + v1[1] * v1[1]) + (v1[2] * v1[2] + v1[3] * v1[3]);
;                     }
;                     s += __shfl_xor(s, 16); s += __shfl_xor(s, 32);
;                     if (fq == 0) ssq_out[(size_t)row * 16 + u.pn * 4 + wc] = s;
;                 }
	v_add_f32_e32 v0, v0, v133
	ds_bpermute_b32 v133, v3, v0
	s_waitcnt lgkmcnt(0)
	v_add_f32_e32 v0, v0, v133
	s_and_saveexec_b64 s[6:7], s[46:47]
	v_add_u32_e32 v133, 0xc00, v134
	global_store_dword v133, v0, s[40:41]
	s_or_b64 exec, exec, s[6:7]
	s_waitcnt vmcnt(19)
	v_lshlrev_b32_e32 v140, 16, v202
	v_and_b32_e32 v141, 0xffff0000, v202
	v_lshlrev_b32_e32 v142, 16, v203
	v_and_b32_e32 v143, 0xffff0000, v203
	v_lshlrev_b32_e32 v144, 16, v204
	v_and_b32_e32 v145, 0xffff0000, v204
	v_lshlrev_b32_e32 v146, 16, v205
	v_and_b32_e32 v147, 0xffff0000, v205
	v_pk_fma_f32 v[140:141], s[88:89], v[60:61], v[140:141]
	v_pk_fma_f32 v[142:143], s[88:89], v[62:63], v[142:143]
	v_pk_fma_f32 v[144:145], s[88:89], v[52:53], v[144:145]
	v_pk_fma_f32 v[146:147], s[88:89], v[54:55], v[146:147]
	v_cvt_pk_bf16_f32 v202, v140, v141
	v_cvt_pk_bf16_f32 v203, v142, v143
	v_cvt_pk_bf16_f32 v204, v144, v145
	v_cvt_pk_bf16_f32 v205, v146, v147
	v_add_u32_e32 v133, 0x40000, v132
	global_store_dwordx4 v133, v[202:205], s[14:15]
	v_mul_f32_e32 v0, v140, v140
	v_mul_f32_e32 v184, v141, v141
	v_fmac_f32_e32 v0, v142, v142
	v_fmac_f32_e32 v184, v143, v143
	v_fmac_f32_e32 v0, v144, v144
	v_fmac_f32_e32 v184, v145, v145
	v_fmac_f32_e32 v0, v146, v146
	v_fmac_f32_e32 v184, v147, v147
	s_waitcnt vmcnt(19)
	v_lshlrev_b32_e32 v140, 16, v206
	v_and_b32_e32 v141, 0xffff0000, v206
	v_lshlrev_b32_e32 v142, 16, v207
	v_and_b32_e32 v143, 0xffff0000, v207
	v_lshlrev_b32_e32 v144, 16, v208
	v_and_b32_e32 v145, 0xffff0000, v208
	v_lshlrev_b32_e32 v146, 16, v209
	v_and_b32_e32 v147, 0xffff0000, v209
	v_pk_fma_f32 v[140:141], s[88:89], v[64:65], v[140:141]
	v_pk_fma_f32 v[142:143], s[88:89], v[66:67], v[142:143]
	v_pk_fma_f32 v[144:145], s[88:89], v[56:57], v[144:145]
	v_pk_fma_f32 v[146:147], s[88:89], v[58:59], v[146:147]
	v_cvt_pk_bf16_f32 v206, v140, v141
	v_cvt_pk_bf16_f32 v207, v142, v143
	v_cvt_pk_bf16_f32 v208, v144, v145
	v_cvt_pk_bf16_f32 v209, v146, v147
	v_add_u32_e32 v133, 0x40100, v132
	global_store_dwordx4 v133, v[206:209], s[14:15]
	v_fmac_f32_e32 v0, v140, v140
	v_fmac_f32_e32 v184, v141, v141
	v_fmac_f32_e32 v0, v142, v142
	v_fmac_f32_e32 v184, v143, v143
	v_fmac_f32_e32 v0, v144, v144
	v_fmac_f32_e32 v184, v145, v145
	v_fmac_f32_e32 v0, v146, v146
	v_fmac_f32_e32 v184, v147, v147
	v_add_f32_e32 v0, v0, v184
	ds_bpermute_b32 v133, v135, v0
	s_waitcnt lgkmcnt(0)
	v_add_f32_e32 v0, v0, v133
	ds_bpermute_b32 v133, v3, v0
	s_waitcnt lgkmcnt(0)
	v_add_f32_e32 v0, v0, v133
	s_and_saveexec_b64 s[6:7], s[46:47]
	v_add_u32_e32 v133, 0x2000, v134
	global_store_dword v133, v0, s[40:41]
	s_or_b64 exec, exec, s[6:7]
	s_waitcnt vmcnt(20)
	v_lshlrev_b32_e32 v140, 16, v210
	v_and_b32_e32 v141, 0xffff0000, v210
	v_lshlrev_b32_e32 v142, 16, v211
	v_and_b32_e32 v143, 0xffff0000, v211
	v_lshlrev_b32_e32 v144, 16, v212
	v_and_b32_e32 v145, 0xffff0000, v212
	v_lshlrev_b32_e32 v146, 16, v213
	v_and_b32_e32 v147, 0xffff0000, v213
	v_pk_fma_f32 v[140:141], s[88:89], v[44:45], v[140:141]
	v_pk_fma_f32 v[142:143], s[88:89], v[46:47], v[142:143]
	v_pk_fma_f32 v[144:145], s[88:89], v[36:37], v[144:145]
	v_pk_fma_f32 v[146:147], s[88:89], v[38:39], v[146:147]
	v_cvt_pk_bf16_f32 v210, v140, v141
	v_cvt_pk_bf16_f32 v211, v142, v143
	v_cvt_pk_bf16_f32 v212, v144, v145
	v_cvt_pk_bf16_f32 v213, v146, v147
	v_add_u32_e32 v133, 0x48000, v132
	global_store_dwordx4 v133, v[210:213], s[14:15]
	v_mul_f32_e32 v0, v140, v140
	v_mul_f32_e32 v184, v141, v141
	v_fmac_f32_e32 v0, v142, v142
	v_fmac_f32_e32 v184, v143, v143
	v_fmac_f32_e32 v0, v144, v144
	v_fmac_f32_e32 v184, v145, v145
	v_fmac_f32_e32 v0, v146, v146
	v_fmac_f32_e32 v184, v147, v147
	s_waitcnt vmcnt(20)
	v_lshlrev_b32_e32 v140, 16, v236
	v_and_b32_e32 v141, 0xffff0000, v236
	v_lshlrev_b32_e32 v142, 16, v237
	v_and_b32_e32 v143, 0xffff0000, v237
	v_lshlrev_b32_e32 v144, 16, v238
	v_and_b32_e32 v145, 0xffff0000, v238
	v_lshlrev_b32_e32 v146, 16, v239
	v_and_b32_e32 v147, 0xffff0000, v239
	v_pk_fma_f32 v[140:141], s[88:89], v[48:49], v[140:141]
	v_pk_fma_f32 v[142:143], s[88:89], v[50:51], v[142:143]
	v_pk_fma_f32 v[144:145], s[88:89], v[40:41], v[144:145]
	v_pk_fma_f32 v[146:147], s[88:89], v[42:43], v[146:147]
	v_cvt_pk_bf16_f32 v236, v140, v141
	v_cvt_pk_bf16_f32 v237, v142, v143
	v_cvt_pk_bf16_f32 v238, v144, v145
	v_cvt_pk_bf16_f32 v239, v146, v147
	v_add_u32_e32 v133, 0x48100, v132
	global_store_dwordx4 v133, v[236:239], s[14:15]
	v_fmac_f32_e32 v0, v140, v140
	v_fmac_f32_e32 v184, v141, v141
	v_fmac_f32_e32 v0, v142, v142
	v_fmac_f32_e32 v184, v143, v143
	v_fmac_f32_e32 v0, v144, v144
	v_fmac_f32_e32 v184, v145, v145
	v_fmac_f32_e32 v0, v146, v146
	v_fmac_f32_e32 v184, v147, v147
	v_add_f32_e32 v0, v0, v184
	ds_bpermute_b32 v133, v135, v0
	s_waitcnt lgkmcnt(0)
	v_add_f32_e32 v0, v0, v133
	ds_bpermute_b32 v133, v3, v0
	s_waitcnt lgkmcnt(0)
	v_add_f32_e32 v0, v0, v133
	s_and_saveexec_b64 s[6:7], s[46:47]
	v_add_u32_e32 v133, 0x2400, v134
	global_store_dword v133, v0, s[40:41]
	s_or_b64 exec, exec, s[6:7]
	s_waitcnt vmcnt(21)
; __device__ __forceinline__ float bf_lo(unsigned w) { return __uint_as_float(w << 16); }
; __device__ __forceinline__ float bf_hi(unsigned w) { return __uint_as_float(w & 0xffff0000u); }
;     static __device__ __forceinline__ u32x4 pack8(const f32x4 a, const f32x4 b) { u32x4 w; w.x = cvtpk(a[0], a[1]); w.y = cvtpk(a[2], a[3]); w.z = cvtpk(b[0], b[1]); w.w = cvtpk(b[2], b[3]); return w; }
;     __device__ __forceinline__ void operator()(const f32x4 (&acc)[2][2][4][2], const pg8::Unit& u, int wr, int wc, int fr_, int fq_) const {
;     ...
;         } else if (MEN(1) && mode == M_RESID) {
;             const float* res = (const float*)i0; const bf16_t* resb = (const bf16_t*)i0; float* outp = (float*)o0; bf16_t* xb = (bf16_t*)o1; const bool rb16 = np == 0;
; #pragma unroll
;             for (int ai = 0; ai < 2; ++ai)
; #pragma unroll
;                 for (int m = 0; m < 4; ++m) {
;                     const int row = rowbase + ai * 128 + m * 16 + fr; float s = 0.f;
; #pragma unroll
;                     for (int bj = 0; bj < 2; ++bj) {
;                         const size_t off = (size_t)row * DM + u.pn * 256 + bj * 128 + cw;
;                         f32x4 a, b;
;                         if (rb16) { const u32x4 w = *(const u32x4*)(resb + off); a = (f32x4){bf_lo(w.x), bf_hi(w.x), bf_lo(w.y), bf_hi(w.y)}; b = (f32x4){bf_lo(w.z), bf_hi(w.z), bf_lo(w.w), bf_hi(w.w)}; }
;                         else { a = *(const f32x4*)(res + off); b = *(const f32x4*)(res + off + 4); }
;                         const f32x4 v0 = a + acc[ai][bj][m][0] * f0, v1 = b + acc[ai][bj][m][1] * f0;
;                         if (outp) { *(f32x4*)(outp + off) = v0; *(f32x4*)(outp + off + 4) = v1; }
;                         if (xb) *(u32x4*)(xb + off) = pack8(v0, v1);
;                         s += (v0[0] * v0[0] + v0[1] * v0[1]) + (v0[2] * v0[2] + v0[3] * v0[3]) + (v1[0] * v1[0] + v1[1] * v1[1]) + (v1[2] * v1[2] + v1[3] * v1[3]);
;                     }
;                     s += __shfl_xor(s, 16); s += __shfl_xor(s, 32);
;                     if (fq == 0) ssq_out[(size_t)row * 16 + u.pn * 4 + wc] = s;
;                 }
	v_lshlrev_b32_e32 v140, 16, v240
	v_and_b32_e32 v141, 0xffff0000, v240
	v_lshlrev_b32_e32 v142, 16, v241
	v_and_b32_e32 v143, 0xffff0000, v241
	v_lshlrev_b32_e32 v144, 16, v242
	v_and_b32_e32 v145, 0xffff0000, v242
	v_lshlrev_b32_e32 v146, 16, v243
	v_and_b32_e32 v147, 0xffff0000, v243
	v_pk_fma_f32 v[140:141], s[88:89], v[28:29], v[140:141]
	v_pk_fma_f32 v[142:143], s[88:89], v[30:31], v[142:143]
	v_pk_fma_f32 v[144:145], s[88:89], v[20:21], v[144:145]
	v_pk_fma_f32 v[146:147], s[88:89], v[22:23], v[146:147]
	v_cvt_pk_bf16_f32 v240, v140, v141
	v_cvt_pk_bf16_f32 v241, v142, v143
	v_cvt_pk_bf16_f32 v242, v144, v145
	v_cvt_pk_bf16_f32 v243, v146, v147
	v_add_u32_e32 v133, 0x50000, v132
	global_store_dwordx4 v133, v[240:243], s[14:15]
	v_mul_f32_e32 v0, v140, v140
	v_mul_f32_e32 v184, v141, v141
	v_fmac_f32_e32 v0, v142, v142
	v_fmac_f32_e32 v184, v143, v143
	v_fmac_f32_e32 v0, v144, v144
	v_fmac_f32_e32 v184, v145, v145
	v_fmac_f32_e32 v0, v146, v146
	v_fmac_f32_e32 v184, v147, v147
	s_waitcnt vmcnt(21)
	v_lshlrev_b32_e32 v140, 16, v244
	v_and_b32_e32 v141, 0xffff0000, v244
	v_lshlrev_b32_e32 v142, 16, v245
	v_and_b32_e32 v143, 0xffff0000, v245
	v_lshlrev_b32_e32 v144, 16, v246
	v_and_b32_e32 v145, 0xffff0000, v246
	v_lshlrev_b32_e32 v146, 16, v247
	v_and_b32_e32 v147, 0xffff0000, v247
	v_pk_fma_f32 v[140:141], s[88:89], v[32:33], v[140:141]
	v_pk_fma_f32 v[142:143], s[88:89], v[34:35], v[142:143]
	v_pk_fma_f32 v[144:145], s[88:89], v[24:25], v[144:145]
	v_pk_fma_f32 v[146:147], s[88:89], v[26:27], v[146:147]
	v_cvt_pk_bf16_f32 v244, v140, v141
	v_cvt_pk_bf16_f32 v245, v142, v143
	v_cvt_pk_bf16_f32 v246, v144, v145
	v_cvt_pk_bf16_f32 v247, v146, v147
	v_add_u32_e32 v133, 0x50100, v132
	global_store_dwordx4 v133, v[244:247], s[14:15]
	v_fmac_f32_e32 v0, v140, v140
	v_fmac_f32_e32 v184, v141, v141
	v_fmac_f32_e32 v0, v142, v142
	v_fmac_f32_e32 v184, v143, v143
	v_fmac_f32_e32 v0, v144, v144
	v_fmac_f32_e32 v184, v145, v145
	v_fmac_f32_e32 v0, v146, v146
	v_fmac_f32_e32 v184, v147, v147
	v_add_f32_e32 v0, v0, v184
	ds_bpermute_b32 v133, v135, v0
	s_waitcnt lgkmcnt(0)
	v_add_f32_e32 v0, v0, v133
	ds_bpermute_b32 v133, v3, v0
	s_waitcnt lgkmcnt(0)
	v_add_f32_e32 v0, v0, v133
	s_and_saveexec_b64 s[6:7], s[46:47]
	v_add_u32_e32 v133, 0x2800, v134
	global_store_dword v133, v0, s[40:41]
	s_or_b64 exec, exec, s[6:7]
	s_waitcnt vmcnt(22)
	v_lshlrev_b32_e32 v140, 16, v248
	v_and_b32_e32 v141, 0xffff0000, v248
	v_lshlrev_b32_e32 v142, 16, v249
	v_and_b32_e32 v143, 0xffff0000, v249
	v_lshlrev_b32_e32 v144, 16, v250
	v_and_b32_e32 v145, 0xffff0000, v250
	v_lshlrev_b32_e32 v146, 16, v251
	v_and_b32_e32 v147, 0xffff0000, v251
	v_pk_fma_f32 v[140:141], s[88:89], v[12:13], v[140:141]
	v_pk_fma_f32 v[142:143], s[88:89], v[14:15], v[142:143]
	v_pk_fma_f32 v[144:145], s[88:89], v[4:5], v[144:145]
	v_pk_fma_f32 v[146:147], s[88:89], v[6:7], v[146:147]
	v_cvt_pk_bf16_f32 v248, v140, v141
	v_cvt_pk_bf16_f32 v249, v142, v143
	v_cvt_pk_bf16_f32 v250, v144, v145
	v_cvt_pk_bf16_f32 v251, v146, v147
	v_add_u32_e32 v133, 0x58000, v132
	global_store_dwordx4 v133, v[248:251], s[14:15]
	v_mul_f32_e32 v0, v140, v140
	v_mul_f32_e32 v184, v141, v141
	v_fmac_f32_e32 v0, v142, v142
	v_fmac_f32_e32 v184, v143, v143
	v_fmac_f32_e32 v0, v144, v144
	v_fmac_f32_e32 v184, v145, v145
	v_fmac_f32_e32 v0, v146, v146
	v_fmac_f32_e32 v184, v147, v147
	s_waitcnt vmcnt(22)
	v_lshlrev_b32_e32 v140, 16, v136
	v_and_b32_e32 v141, 0xffff0000, v136
	v_lshlrev_b32_e32 v142, 16, v137
	v_and_b32_e32 v143, 0xffff0000, v137
	v_lshlrev_b32_e32 v144, 16, v138
	v_and_b32_e32 v145, 0xffff0000, v138
	v_lshlrev_b32_e32 v146, 16, v139
	v_and_b32_e32 v147, 0xffff0000, v139
	v_pk_fma_f32 v[140:141], s[88:89], v[16:17], v[140:141]
	v_pk_fma_f32 v[142:143], s[88:89], v[18:19], v[142:143]
	v_pk_fma_f32 v[144:145], s[88:89], v[8:9], v[144:145]
	v_pk_fma_f32 v[146:147], s[88:89], v[10:11], v[146:147]
	v_cvt_pk_bf16_f32 v136, v140, v141
	v_cvt_pk_bf16_f32 v137, v142, v143
	v_cvt_pk_bf16_f32 v138, v144, v145
	v_cvt_pk_bf16_f32 v139, v146, v147
	v_add_u32_e32 v133, 0x58100, v132
	global_store_dwordx4 v133, v[136:139], s[14:15]
	v_fmac_f32_e32 v0, v140, v140
	v_fmac_f32_e32 v184, v141, v141
	v_fmac_f32_e32 v0, v142, v142
	v_fmac_f32_e32 v184, v143, v143
	v_fmac_f32_e32 v0, v144, v144
	v_fmac_f32_e32 v184, v145, v145
	v_fmac_f32_e32 v0, v146, v146
	v_fmac_f32_e32 v184, v147, v147
	v_add_f32_e32 v0, v0, v184
	ds_bpermute_b32 v133, v135, v0
	s_waitcnt lgkmcnt(0)
	v_add_f32_e32 v0, v0, v133
	ds_bpermute_b32 v133, v3, v0
	s_waitcnt lgkmcnt(0)
	v_add_f32_e32 v0, v0, v133
	s_and_saveexec_b64 s[6:7], s[46:47]
	v_add_u32_e32 v133, 0x2c00, v134
	global_store_dword v133, v0, s[40:41]
	s_or_b64 exec, exec, s[6:7]
	s_branch .LBB0_795
.Lresid_generic:
	v_add_u32_e32 v160, s2, v193
	v_ashrrev_i32_e32 v161, 31, v160
	s_waitcnt lgkmcnt(0)
	v_ashrrev_i32_e32 v3, 31, v2
	v_lshlrev_b64 v[132:133], 10, v[160:161]
	v_lshl_add_u64 v[132:133], v[132:133], 0, v[2:3]
	v_readlane_b32 s14, v255, 25
	v_lshl_add_u64 v[140:141], v[132:133], 0, s[92:93]
	v_readlane_b32 s15, v255, 26
	s_mov_b64 s[6:7], -1
	s_and_b64 vcc, exec, s[14:15]
	v_lshl_add_u64 v[162:163], v[140:141], 2, s[4:5]
	s_cbranch_vccz .LBB0_652
	global_load_dwordx4 v[136:139], v[162:163], off offset:16
	global_load_dwordx4 v[132:135], v[162:163], off
	s_mov_b64 s[6:7], 0

;     static __device__ __forceinline__ float rowsum(const float* ssq, int row, int np) {
;         const f32x4* p = (const f32x4*)(ssq + (size_t)row * np);
;         float s = 0.f;
;         for (int i = 0; i < np / 4; ++i) { const f32x4 v = p[i]; s += (v[0] + v[1]) + (v[2] + v[3]); }
;         return s;
;     }
;     __device__ __forceinline__ void row_scales(int rowbase, int lane, int fr, float (&rs)[2]) const {
;         rs[0] = rsqrtf(rowsum(ssq, rowbase + lane, np) * inv_dim + EPS); rs[1] = rsqrtf(rowsum(ssq, rowbase + 128 + lane, np) * inv_dim + EPS);
;     }
.LBB0_796:
	s_andn2_b64 vcc, exec, s[6:7]
	s_cbranch_vccnz .LBB0_804
	v_readlane_b32 s6, v255, 16
	v_readlane_b32 s7, v255, 17
	s_waitcnt lgkmcnt(0)
	v_add_u32_e32 v3, s2, v194
	v_ashrrev_i32_e32 v134, 31, v3
	v_cndmask_b32_e64 v0, 0, 1, s[6:7]
	v_cmp_ne_u32_e64 s[40:41], 1, v0
	s_andn2_b64 vcc, exec, s[6:7]
	v_mov_b32_e32 v0, 0
	s_cbranch_vccnz .LBB0_800
	v_readlane_b32 s6, v255, 22
	v_readlane_b32 s7, v255, 23
	v_readlane_b32 s14, v255, 61
	v_readlane_b32 s15, v255, 62
	v_mov_b64_e32 v[132:133], s[6:7]
	v_mad_u64_u32 v[132:133], s[6:7], s14, v3, v[132:133]
	v_mul_lo_u32 v0, s14, v134
	v_mul_lo_u32 v134, s15, v3
	v_add3_u32 v133, v134, v133, v0
	v_mov_b32_e32 v0, 0
	v_readlane_b32 s1, v255, 42
	s_cmp_lg_u32 s1, 4
	s_cbranch_scc1 .LBB0_799
	global_load_dwordx4 v[160:163], v[132:133], off
	global_load_dwordx4 v[164:167], v[132:133], off offset:16
	global_load_dwordx4 v[168:171], v[132:133], off offset:32
	global_load_dwordx4 v[172:175], v[132:133], off offset:48
	v_add_u32_e32 v3, 0x80, v3
	v_readlane_b32 s6, v255, 22
	v_ashrrev_i32_e32 v132, 31, v3
	v_readlane_b32 s14, v255, 61
	v_readlane_b32 s7, v255, 23
	v_readlane_b32 s15, v255, 62
	v_mul_lo_u32 v134, s14, v132
	v_mov_b64_e32 v[132:133], s[6:7]
	v_mul_lo_u32 v135, s15, v3
	v_mad_u64_u32 v[132:133], s[6:7], s14, v3, v[132:133]
	v_add3_u32 v133, v135, v133, v134
	global_load_dwordx4 v[176:179], v[132:133], off
	global_load_dwordx4 v[180:183], v[132:133], off offset:16
	global_load_dwordx4 v[202:205], v[132:133], off offset:32
	global_load_dwordx4 v[206:209], v[132:133], off offset:48
	v_mov_b32_e32 v135, 0
	s_waitcnt vmcnt(4)
	v_add_f32_e32 v134, v160, v161
	v_add_f32_e32 v136, v162, v163
	v_add_f32_e32 v134, v134, v136
	v_add_f32_e32 v0, v0, v134
	v_add_f32_e32 v134, v164, v165
	v_add_f32_e32 v136, v166, v167
	v_add_f32_e32 v134, v134, v136
	v_add_f32_e32 v0, v0, v134
	v_add_f32_e32 v134, v168, v169
	v_add_f32_e32 v136, v170, v171
	v_add_f32_e32 v134, v134, v136
	v_add_f32_e32 v0, v0, v134
	v_add_f32_e32 v134, v172, v173
	v_add_f32_e32 v136, v174, v175
	v_add_f32_e32 v134, v134, v136
	v_add_f32_e32 v0, v0, v134
	s_waitcnt vmcnt(0)
	v_add_f32_e32 v134, v176, v177
	v_add_f32_e32 v136, v178, v179
	v_add_f32_e32 v3, v134, v136
	v_add_f32_e32 v135, v135, v3
	v_add_f32_e32 v134, v180, v181
	v_add_f32_e32 v136, v182, v183
	v_add_f32_e32 v3, v134, v136
	v_add_f32_e32 v135, v135, v3
	v_add_f32_e32 v134, v202, v203
	v_add_f32_e32 v136, v204, v205
	v_add_f32_e32 v3, v134, v136
	v_add_f32_e32 v135, v135, v3
	v_add_f32_e32 v134, v206, v207
	v_add_f32_e32 v136, v208, v209
	v_add_f32_e32 v3, v134, v136
	v_add_f32_e32 v135, v135, v3
	s_branch .LBB0_803
